# spatial-gating prompt item: runs of read->wait->MFMA through one fragment register turned into 6 batched LDS reads + 6 MFMAs
# baseline (speedup 1.0000x reference)
.LBB0_117:
	v_mov_b32_e32 v32, v148
	v_mov_b32_e32 v33, v149
	v_mov_b32_e32 v34, v150
	v_mov_b32_e32 v35, v151
	v_mov_b32_e32 v36, v152
	v_mov_b32_e32 v37, v153
	v_mov_b32_e32 v38, v154
	v_mov_b32_e32 v39, v155
	v_readlane_b32 s68, v248, 29
	v_readlane_b32 s69, v248, 30
	s_nop 0
	s_nop 0
	v_cndmask_b32_e64 v36, v36, 0, s[68:69]
	v_readlane_b32 s68, v248, 31
	v_readlane_b32 s69, v248, 32
	v_bfe_u32 v40, v36, 16, 1
	v_add3_u32 v36, v36, v40, s33
	v_cndmask_b32_e64 v37, v37, 0, s[68:69]
	v_bfe_u32 v40, v37, 16, 1
	v_readlane_b32 s68, v248, 33
	v_add3_u32 v37, v37, v40, s33
	v_lshrrev_b32_e32 v36, 16, v36
	v_readlane_b32 s69, v248, 34
	v_and_or_b32 v36, v37, s29, v36
	s_nop 0
	v_cndmask_b32_e64 v37, v38, 0, s[68:69]
	v_readlane_b32 s68, v248, 35
	v_readlane_b32 s69, v248, 36
	s_nop 1
	v_cndmask_b32_e64 v38, v39, 0, s[68:69]
	v_readlane_b32 s68, v248, 37
	v_bfe_u32 v39, v37, 16, 1
	v_readlane_b32 s69, v248, 38
	v_add3_u32 v37, v37, v39, s33
	v_bfe_u32 v39, v38, 16, 1
	v_cndmask_b32_e64 v32, v32, 0, s[68:69]
	v_readlane_b32 s68, v248, 39
	v_add3_u32 v38, v38, v39, s33
	v_lshrrev_b32_e32 v37, 16, v37
	v_readlane_b32 s69, v248, 40
	v_and_or_b32 v37, v38, s29, v37
	v_bfe_u32 v38, v32, 16, 1
	v_cndmask_b32_e64 v33, v33, 0, s[68:69]
	v_add3_u32 v32, v32, v38, s33
	v_bfe_u32 v38, v33, 16, 1
	v_readlane_b32 s68, v248, 41
	v_add3_u32 v33, v33, v38, s33
	v_lshrrev_b32_e32 v32, 16, v32
	v_readlane_b32 s69, v248, 42
	v_and_or_b32 v38, v33, s29, v32
	s_nop 0
	v_cndmask_b32_e64 v32, v34, 0, s[68:69]
	v_readlane_b32 s68, v248, 43
	v_readlane_b32 s69, v248, 44
	v_bfe_u32 v34, v32, 16, 1
	v_add3_u32 v32, v32, v34, s33
	v_cndmask_b32_e64 v33, v35, 0, s[68:69]
	v_bfe_u32 v34, v33, 16, 1
	v_add3_u32 v33, v33, v34, s33
	v_lshrrev_b32_e32 v32, 16, v32
	v_and_or_b32 v39, v33, s29, v32
	ds_read_b128 v[204:207], v111 offset:2688
	ds_read_b128 v[208:211], v111 offset:7040
	ds_read_b128 v[212:215], v110 offset:2688
	ds_read_b128 v[216:219], v109 offset:2688
	ds_read_b128 v[240:243], v108 offset:2688
	ds_read_b128 v[244:247], v103 offset:2688
	s_waitcnt lgkmcnt(5)
	v_mfma_f32_16x16x32_bf16 v[28:31], v[36:39], v[204:207], v[28:31]
	s_waitcnt lgkmcnt(4)
	v_mfma_f32_16x16x32_bf16 v[24:27], v[36:39], v[208:211], v[24:27]
	s_waitcnt lgkmcnt(3)
	v_mfma_f32_16x16x32_bf16 v[20:23], v[36:39], v[212:215], v[20:23]
	s_waitcnt lgkmcnt(2)
	v_mfma_f32_16x16x32_bf16 v[16:19], v[36:39], v[216:219], v[16:19]
	s_waitcnt lgkmcnt(1)
	v_mfma_f32_16x16x32_bf16 v[12:15], v[36:39], v[240:243], v[12:15]
	s_waitcnt lgkmcnt(0)
	v_mfma_f32_16x16x32_bf16 v[8:11], v[36:39], v[244:247], v[8:11]
	s_or_b64 exec, exec, s[2:3]
	s_and_saveexec_b64 s[2:3], s[62:63]
	s_cbranch_execnz .LBB0_121
	s_branch .LBB0_122

.LBB0_119:
	v_mov_b32_e32 v32, v156
	v_mov_b32_e32 v33, v157
	v_mov_b32_e32 v34, v158
	v_mov_b32_e32 v35, v159
	v_mov_b32_e32 v36, v160
	v_mov_b32_e32 v37, v161
	v_mov_b32_e32 v38, v162
	v_mov_b32_e32 v39, v163
	v_readlane_b32 s68, v249, 55
	v_readlane_b32 s69, v249, 56
	s_nop 0
	s_nop 0
	v_cndmask_b32_e64 v36, v36, 0, s[68:69]
	v_readlane_b32 s68, v248, 15
	v_readlane_b32 s69, v248, 16
	v_bfe_u32 v40, v36, 16, 1
	v_add3_u32 v36, v36, v40, s33
	v_cndmask_b32_e64 v37, v37, 0, s[68:69]
	v_bfe_u32 v40, v37, 16, 1
	v_readlane_b32 s68, v248, 17
	v_add3_u32 v37, v37, v40, s33
	v_lshrrev_b32_e32 v36, 16, v36
	v_readlane_b32 s69, v248, 18
	v_and_or_b32 v36, v37, s29, v36
	s_nop 0
	v_cndmask_b32_e64 v37, v38, 0, s[68:69]
	v_readlane_b32 s68, v248, 19
	v_readlane_b32 s69, v248, 20
	s_nop 1
	v_cndmask_b32_e64 v38, v39, 0, s[68:69]
	v_readlane_b32 s68, v248, 21
	v_bfe_u32 v39, v37, 16, 1
	v_readlane_b32 s69, v248, 22
	v_add3_u32 v37, v37, v39, s33
	v_bfe_u32 v39, v38, 16, 1
	v_cndmask_b32_e64 v32, v32, 0, s[68:69]
	v_readlane_b32 s68, v248, 23
	v_add3_u32 v38, v38, v39, s33
	v_lshrrev_b32_e32 v37, 16, v37
	v_readlane_b32 s69, v248, 24
	v_and_or_b32 v37, v38, s29, v37
	v_bfe_u32 v38, v32, 16, 1
	v_cndmask_b32_e64 v33, v33, 0, s[68:69]
	v_add3_u32 v32, v32, v38, s33
	v_bfe_u32 v38, v33, 16, 1
	v_readlane_b32 s68, v248, 25
	v_add3_u32 v33, v33, v38, s33
	v_lshrrev_b32_e32 v32, 16, v32
	v_readlane_b32 s69, v248, 26
	v_and_or_b32 v38, v33, s29, v32
	s_nop 0
	v_cndmask_b32_e64 v32, v34, 0, s[68:69]
	v_readlane_b32 s68, v248, 27
	v_readlane_b32 s69, v248, 28
	v_bfe_u32 v34, v32, 16, 1
	v_add3_u32 v32, v32, v34, s33
	v_cndmask_b32_e64 v33, v35, 0, s[68:69]
	v_bfe_u32 v34, v33, 16, 1
	v_add3_u32 v33, v33, v34, s33
	v_lshrrev_b32_e32 v32, 16, v32
	v_and_or_b32 v39, v33, s29, v32
	ds_read_b128 v[204:207], v111 offset:2624
	ds_read_b128 v[208:211], v111 offset:6976
	ds_read_b128 v[212:215], v110 offset:2624
	ds_read_b128 v[216:219], v109 offset:2624
	ds_read_b128 v[240:243], v108 offset:2624
	ds_read_b128 v[244:247], v103 offset:2624
	s_waitcnt lgkmcnt(5)
	v_mfma_f32_16x16x32_bf16 v[28:31], v[36:39], v[204:207], v[28:31]
	s_waitcnt lgkmcnt(4)
	v_mfma_f32_16x16x32_bf16 v[24:27], v[36:39], v[208:211], v[24:27]
	s_waitcnt lgkmcnt(3)
	v_mfma_f32_16x16x32_bf16 v[20:23], v[36:39], v[212:215], v[20:23]
	s_waitcnt lgkmcnt(2)
	v_mfma_f32_16x16x32_bf16 v[16:19], v[36:39], v[216:219], v[16:19]
	s_waitcnt lgkmcnt(1)
	v_mfma_f32_16x16x32_bf16 v[12:15], v[36:39], v[240:243], v[12:15]
	s_waitcnt lgkmcnt(0)
	v_mfma_f32_16x16x32_bf16 v[8:11], v[36:39], v[244:247], v[8:11]
	s_or_b64 exec, exec, s[2:3]
	s_and_saveexec_b64 s[2:3], s[44:45]
	s_cbranch_execnz .LBB0_117

.LBB0_121:
	v_mov_b32_e32 v32, v164
	v_mov_b32_e32 v33, v165
	v_mov_b32_e32 v34, v166
	v_mov_b32_e32 v35, v167
	v_mov_b32_e32 v36, v168
	v_mov_b32_e32 v37, v169
	v_mov_b32_e32 v38, v170
	v_mov_b32_e32 v39, v171
	v_readlane_b32 s68, v248, 45
	v_readlane_b32 s69, v248, 46
	s_nop 0
	v_cndmask_b32_e64 v32, v32, 0, s[72:73]
	s_nop 0
	v_cndmask_b32_e64 v36, v36, 0, s[68:69]
	v_readlane_b32 s68, v248, 47
	v_readlane_b32 s69, v248, 48
	v_bfe_u32 v40, v36, 16, 1
	v_add3_u32 v36, v36, v40, s33
	v_cndmask_b32_e64 v37, v37, 0, s[68:69]
	v_bfe_u32 v40, v37, 16, 1
	v_readlane_b32 s68, v248, 49
	v_add3_u32 v37, v37, v40, s33
	v_lshrrev_b32_e32 v36, 16, v36
	v_readlane_b32 s69, v248, 50
	v_and_or_b32 v36, v37, s29, v36
	v_cndmask_b32_e64 v33, v33, 0, s[74:75]
	v_cndmask_b32_e64 v37, v38, 0, s[68:69]
	v_readlane_b32 s68, v248, 51
	v_readlane_b32 s69, v248, 52
	s_nop 1
	v_cndmask_b32_e64 v38, v39, 0, s[68:69]
	v_bfe_u32 v39, v37, 16, 1
	v_add3_u32 v37, v37, v39, s33
	v_bfe_u32 v39, v38, 16, 1
	v_add3_u32 v38, v38, v39, s33
	v_lshrrev_b32_e32 v37, 16, v37
	v_and_or_b32 v37, v38, s29, v37
	v_bfe_u32 v38, v32, 16, 1
	v_add3_u32 v32, v32, v38, s33
	v_bfe_u32 v38, v33, 16, 1
	v_add3_u32 v33, v33, v38, s33
	v_lshrrev_b32_e32 v32, 16, v32
	v_and_or_b32 v38, v33, s29, v32
	v_cndmask_b32_e64 v32, v34, 0, s[76:77]
	v_cndmask_b32_e64 v33, v35, 0, s[78:79]
	v_bfe_u32 v34, v32, 16, 1
	v_add3_u32 v32, v32, v34, s33
	v_bfe_u32 v34, v33, 16, 1
	v_add3_u32 v33, v33, v34, s33
	v_lshrrev_b32_e32 v32, 16, v32
	v_and_or_b32 v39, v33, s29, v32
	ds_read_b128 v[204:207], v111 offset:2752
	ds_read_b128 v[208:211], v111 offset:7104
	ds_read_b128 v[212:215], v110 offset:2752
	ds_read_b128 v[216:219], v109 offset:2752
	ds_read_b128 v[240:243], v108 offset:2752
	ds_read_b128 v[244:247], v103 offset:2752
	s_waitcnt lgkmcnt(5)
	v_mfma_f32_16x16x32_bf16 v[28:31], v[36:39], v[204:207], v[28:31]
	s_waitcnt lgkmcnt(4)
	v_mfma_f32_16x16x32_bf16 v[24:27], v[36:39], v[208:211], v[24:27]
	s_waitcnt lgkmcnt(3)
	v_mfma_f32_16x16x32_bf16 v[20:23], v[36:39], v[212:215], v[20:23]
	s_waitcnt lgkmcnt(2)
	v_mfma_f32_16x16x32_bf16 v[16:19], v[36:39], v[216:219], v[16:19]
	s_waitcnt lgkmcnt(1)
	v_mfma_f32_16x16x32_bf16 v[12:15], v[36:39], v[240:243], v[12:15]
	s_waitcnt lgkmcnt(0)
	v_mfma_f32_16x16x32_bf16 v[8:11], v[36:39], v[244:247], v[8:11]

.LBB0_125:
	v_mov_b32_e32 v116, v180
	v_mov_b32_e32 v117, v181
	v_mov_b32_e32 v118, v182
	v_mov_b32_e32 v119, v183
	v_mov_b32_e32 v120, v184
	v_mov_b32_e32 v121, v185
	v_mov_b32_e32 v122, v186
	v_mov_b32_e32 v123, v187
	s_nop 0
	v_cndmask_b32_e64 v81, v120, 0, s[20:21]
	v_cndmask_b32_e64 v82, v121, 0, s[22:23]
	v_bfe_u32 v83, v81, 16, 1
	v_add3_u32 v81, v81, v83, s33
	v_bfe_u32 v83, v82, 16, 1
	v_add3_u32 v82, v82, v83, s33
	v_lshrrev_b32_e32 v81, 16, v81
	v_and_or_b32 v120, v82, s29, v81
	v_cndmask_b32_e64 v81, v122, 0, s[26:27]
	v_cndmask_b32_e64 v82, v123, 0, s[66:67]
	v_bfe_u32 v83, v81, 16, 1
	v_add3_u32 v81, v81, v83, s33
	v_bfe_u32 v83, v82, 16, 1
	v_add3_u32 v82, v82, v83, s33
	v_lshrrev_b32_e32 v81, 16, v81
	v_and_or_b32 v121, v82, s29, v81
	v_cndmask_b32_e64 v81, v116, 0, s[30:31]
	v_cndmask_b32_e64 v82, v117, 0, s[34:35]
	v_bfe_u32 v83, v81, 16, 1
	v_add3_u32 v81, v81, v83, s33
	v_bfe_u32 v83, v82, 16, 1
	v_add3_u32 v82, v82, v83, s33
	v_lshrrev_b32_e32 v81, 16, v81
	v_and_or_b32 v122, v82, s29, v81
	v_cndmask_b32_e64 v81, v118, 0, s[36:37]
	v_cndmask_b32_e64 v82, v119, 0, s[38:39]
	v_bfe_u32 v83, v81, 16, 1
	v_add3_u32 v81, v81, v83, s33
	v_bfe_u32 v83, v82, 16, 1
	v_add3_u32 v82, v82, v83, s33
	v_lshrrev_b32_e32 v81, 16, v81
	v_and_or_b32 v123, v82, s29, v81
	ds_read_b128 v[204:207], v111 offset:2688
	ds_read_b128 v[208:211], v111 offset:7040
	ds_read_b128 v[212:215], v110 offset:2688
	ds_read_b128 v[216:219], v109 offset:2688
	ds_read_b128 v[240:243], v108 offset:2688
	ds_read_b128 v[244:247], v103 offset:2688
	s_waitcnt lgkmcnt(5)
	v_mfma_f32_16x16x32_bf16 v[52:55], v[120:123], v[204:207], v[52:55]
	s_waitcnt lgkmcnt(4)
	v_mfma_f32_16x16x32_bf16 v[48:51], v[120:123], v[208:211], v[48:51]
	s_waitcnt lgkmcnt(3)
	v_mfma_f32_16x16x32_bf16 v[44:47], v[120:123], v[212:215], v[44:47]
	s_waitcnt lgkmcnt(2)
	v_mfma_f32_16x16x32_bf16 v[40:43], v[120:123], v[216:219], v[40:43]
	s_waitcnt lgkmcnt(1)
	v_mfma_f32_16x16x32_bf16 v[36:39], v[120:123], v[240:243], v[36:39]
	s_waitcnt lgkmcnt(0)
	v_mfma_f32_16x16x32_bf16 v[32:35], v[120:123], v[244:247], v[32:35]
	s_or_b64 exec, exec, s[2:3]
	s_and_saveexec_b64 s[2:3], s[40:41]
	s_cbranch_execz .LBB0_113
	s_branch .LBB0_129

.LBB0_127:
	v_mov_b32_e32 v116, v188
	v_mov_b32_e32 v117, v189
	v_mov_b32_e32 v118, v190
	v_mov_b32_e32 v119, v191
	v_mov_b32_e32 v120, v192
	v_mov_b32_e32 v121, v193
	v_mov_b32_e32 v122, v194
	v_mov_b32_e32 v123, v195
	s_nop 0
	v_cndmask_b32_e64 v81, v120, 0, s[4:5]
	v_cndmask_b32_e64 v82, v121, 0, s[60:61]
	v_bfe_u32 v83, v81, 16, 1
	v_add3_u32 v81, v81, v83, s33
	v_bfe_u32 v83, v82, 16, 1
	v_add3_u32 v82, v82, v83, s33
	v_lshrrev_b32_e32 v81, 16, v81
	v_and_or_b32 v120, v82, s29, v81
	v_cndmask_b32_e64 v81, v122, 0, s[8:9]
	v_cndmask_b32_e64 v82, v123, 0, s[0:1]
	v_bfe_u32 v83, v81, 16, 1
	v_add3_u32 v81, v81, v83, s33
	v_bfe_u32 v83, v82, 16, 1
	v_add3_u32 v82, v82, v83, s33
	v_lshrrev_b32_e32 v81, 16, v81
	v_and_or_b32 v121, v82, s29, v81
	v_cndmask_b32_e64 v81, v116, 0, s[10:11]
	v_cndmask_b32_e64 v82, v117, 0, s[12:13]
	v_bfe_u32 v83, v81, 16, 1
	v_add3_u32 v81, v81, v83, s33
	v_bfe_u32 v83, v82, 16, 1
	v_add3_u32 v82, v82, v83, s33
	v_lshrrev_b32_e32 v81, 16, v81
	v_and_or_b32 v122, v82, s29, v81
	v_cndmask_b32_e64 v81, v118, 0, s[14:15]
	v_cndmask_b32_e64 v82, v119, 0, s[16:17]
	v_bfe_u32 v83, v81, 16, 1
	v_add3_u32 v81, v81, v83, s33
	v_bfe_u32 v83, v82, 16, 1
	v_add3_u32 v82, v82, v83, s33
	v_lshrrev_b32_e32 v81, 16, v81
	v_and_or_b32 v123, v82, s29, v81
	ds_read_b128 v[204:207], v111 offset:2624
	ds_read_b128 v[208:211], v111 offset:6976
	ds_read_b128 v[212:215], v110 offset:2624
	ds_read_b128 v[216:219], v109 offset:2624
	ds_read_b128 v[240:243], v108 offset:2624
	ds_read_b128 v[244:247], v103 offset:2624
	s_waitcnt lgkmcnt(5)
	v_mfma_f32_16x16x32_bf16 v[52:55], v[120:123], v[204:207], v[52:55]
	s_waitcnt lgkmcnt(4)
	v_mfma_f32_16x16x32_bf16 v[48:51], v[120:123], v[208:211], v[48:51]
	s_waitcnt lgkmcnt(3)
	v_mfma_f32_16x16x32_bf16 v[44:47], v[120:123], v[212:215], v[44:47]
	s_waitcnt lgkmcnt(2)
	v_mfma_f32_16x16x32_bf16 v[40:43], v[120:123], v[216:219], v[40:43]
	s_waitcnt lgkmcnt(1)
	v_mfma_f32_16x16x32_bf16 v[36:39], v[120:123], v[240:243], v[36:39]
	s_waitcnt lgkmcnt(0)
	v_mfma_f32_16x16x32_bf16 v[32:35], v[120:123], v[244:247], v[32:35]
	s_or_b64 exec, exec, s[2:3]
	s_and_saveexec_b64 s[2:3], s[18:19]
	s_cbranch_execnz .LBB0_125
